# rmsnorm bodies: the 12 gain/scale/shift vector loads issued together (fresh registers for groups 1-3), per-block drains replaced by counted waits
# speedup vs baseline: 1.0087x; 1.0087x over previous
.LBB0_83:
	s_or_b64 exec, exec, s[46:47]
	v_add_u32_e32 v130, 0xffffdffd, v154
	v_lshrrev_b32_e32 v130, 11, v130
	v_add_u32_e32 v130, 1, v130
	v_cndmask_b32_e32 v130, 0, v130, vcc
	s_and_b64 s[0:1], exec, s[0:1]
	v_add_u32_e32 v132, s3, v130
	s_or_b64 s[30:31], s[0:1], s[30:31]
	v_mov_b64_e32 v[130:131], s[84:85]
	s_mov_b32 s0, 0x9000
	v_mad_u64_u32 v[130:131], s[0:1], v132, s0, v[130:131]
	s_waitcnt vmcnt(0)
	v_mov_b32_e32 v132, v118
	v_mov_b32_e32 v133, v126
	v_pk_mul_f32 v[132:133], v[132:133], v[132:133]
	v_mov_b32_e32 v134, v119
	v_mov_b32_e32 v135, v127
	v_pk_fma_f32 v[132:133], v[134:135], v[134:135], v[132:133]
	v_mov_b32_e32 v134, v120
	v_mov_b32_e32 v135, v128
	v_pk_fma_f32 v[132:133], v[134:135], v[134:135], v[132:133]
	v_mov_b32_e32 v134, v121
	v_mov_b32_e32 v135, v129
	v_pk_fma_f32 v[132:133], v[134:135], v[134:135], v[132:133]
	v_mov_b32_e32 v134, v52
	v_mov_b32_e32 v135, v98
	v_pk_mul_f32 v[134:135], v[134:135], v[134:135]
	v_mov_b32_e32 v136, v53
	v_mov_b32_e32 v137, v99
	v_pk_fma_f32 v[134:135], v[136:137], v[136:137], v[134:135]
	v_mov_b32_e32 v136, v54
	v_mov_b32_e32 v137, v100
	v_pk_fma_f32 v[134:135], v[136:137], v[136:137], v[134:135]
	v_mov_b32_e32 v136, v55
	v_mov_b32_e32 v137, v101
	v_pk_fma_f32 v[134:135], v[136:137], v[136:137], v[134:135]
	v_mov_b32_e32 v136, v110
	v_mov_b32_e32 v137, v122
	v_pk_mul_f32 v[136:137], v[136:137], v[136:137]
	v_mov_b32_e32 v138, v111
	v_mov_b32_e32 v139, v123
	v_pk_fma_f32 v[136:137], v[138:139], v[138:139], v[136:137]
	v_mov_b32_e32 v138, v112
	v_mov_b32_e32 v139, v124
	v_pk_fma_f32 v[136:137], v[138:139], v[138:139], v[136:137]
	v_mov_b32_e32 v138, v113
	v_mov_b32_e32 v139, v125
	v_pk_fma_f32 v[136:137], v[138:139], v[138:139], v[136:137]
	v_mov_b32_e32 v138, v8
	v_mov_b32_e32 v139, v80
	v_pk_mul_f32 v[138:139], v[138:139], v[138:139]
	v_mov_b32_e32 v140, v9
	v_mov_b32_e32 v141, v81
	v_pk_fma_f32 v[138:139], v[140:141], v[140:141], v[138:139]
	v_mov_b32_e32 v140, v10
	v_mov_b32_e32 v141, v82
	v_pk_fma_f32 v[138:139], v[140:141], v[140:141], v[138:139]
	v_mov_b32_e32 v140, v11
	v_mov_b32_e32 v141, v83
	v_pk_fma_f32 v[138:139], v[140:141], v[140:141], v[138:139]
	v_mov_b32_e32 v140, v92
	v_mov_b32_e32 v141, v114
	v_pk_mul_f32 v[140:141], v[140:141], v[140:141]
	v_mov_b32_e32 v162, v93
	v_mov_b32_e32 v163, v115
	v_pk_fma_f32 v[140:141], v[162:163], v[162:163], v[140:141]
	v_mov_b32_e32 v162, v94
	v_mov_b32_e32 v163, v116
	v_pk_fma_f32 v[140:141], v[162:163], v[162:163], v[140:141]
	v_mov_b32_e32 v162, v95
	v_mov_b32_e32 v163, v117
	v_pk_fma_f32 v[140:141], v[162:163], v[162:163], v[140:141]
	v_mov_b32_e32 v162, v4
	v_mov_b32_e32 v163, v40
	v_pk_mul_f32 v[162:163], v[162:163], v[162:163]
	v_mov_b32_e32 v164, v5
	v_mov_b32_e32 v165, v41
	v_pk_fma_f32 v[162:163], v[164:165], v[164:165], v[162:163]
	v_mov_b32_e32 v164, v6
	v_mov_b32_e32 v165, v42
	v_pk_fma_f32 v[162:163], v[164:165], v[164:165], v[162:163]
	v_mov_b32_e32 v164, v7
	v_mov_b32_e32 v165, v43
	v_pk_fma_f32 v[162:163], v[164:165], v[164:165], v[162:163]
	v_mov_b32_e32 v164, v64
	v_mov_b32_e32 v165, v106
	v_pk_mul_f32 v[164:165], v[164:165], v[164:165]
	v_mov_b32_e32 v166, v65
	v_mov_b32_e32 v167, v107
	v_pk_fma_f32 v[164:165], v[166:167], v[166:167], v[164:165]
	v_mov_b32_e32 v166, v66
	v_mov_b32_e32 v167, v108
	v_pk_fma_f32 v[164:165], v[166:167], v[166:167], v[164:165]
	v_mov_b32_e32 v166, v67
	v_mov_b32_e32 v167, v109
	v_pk_fma_f32 v[164:165], v[166:167], v[166:167], v[164:165]
	v_mov_b32_e32 v166, v0
	v_mov_b32_e32 v167, v16
	v_pk_mul_f32 v[166:167], v[166:167], v[166:167]
	v_mov_b32_e32 v168, v1
	v_mov_b32_e32 v169, v17
	v_pk_fma_f32 v[166:167], v[168:169], v[168:169], v[166:167]
	v_mov_b32_e32 v168, v2
	v_mov_b32_e32 v169, v18
	v_pk_fma_f32 v[166:167], v[168:169], v[168:169], v[166:167]
	v_mov_b32_e32 v168, v3
	v_mov_b32_e32 v169, v19
	v_pk_fma_f32 v[166:167], v[168:169], v[168:169], v[166:167]
	v_mov_b32_e32 v168, v136
	v_mov_b32_e32 v169, v132
	v_mov_b32_e32 v132, v137
	v_pk_add_f32 v[132:133], v[168:169], v[132:133]
	v_mov_b32_e32 v136, v139
	v_mov_b32_e32 v137, v135
	v_pk_add_f32 v[132:133], v[136:137], v[132:133]
	v_mov_b32_e32 v139, v134
	v_pk_add_f32 v[132:133], v[138:139], v[132:133]
	ds_bpermute_b32 v135, v149, v133
	ds_bpermute_b32 v134, v149, v132
	s_mov_b64 s[0:1], 0x1000
	v_lshl_add_u64 v[156:157], v[130:131], 0, s[0:1]
	s_mov_b32 s0, 0x358637bd
	s_mov_b32 s36, 0x3a800000
	s_waitcnt lgkmcnt(0)
	v_pk_add_f32 v[132:133], v[132:133], v[134:135]
	ds_bpermute_b32 v135, v151, v133
	ds_bpermute_b32 v134, v151, v132
	s_mov_b32 s24, 0x800000
	v_mov_b32_e32 v137, v163
	v_lshl_add_u64 v[180:181], v[130:131], 0, v[96:97]
	v_add_u32_e32 v176, -3, v154
	s_waitcnt lgkmcnt(0)
	v_pk_add_f32 v[132:133], v[132:133], v[134:135]
	ds_bpermute_b32 v135, v153, v133
	ds_bpermute_b32 v134, v153, v132
	v_ashrrev_i32_e32 v177, 31, v176
	v_ashrrev_i32_e32 v155, 31, v154
	s_mov_b32 s82, 0x800000
	s_waitcnt lgkmcnt(0)
	v_pk_add_f32 v[132:133], v[132:133], v[134:135]
	ds_bpermute_b32 v135, v159, v133
	ds_bpermute_b32 v134, v159, v132
	s_waitcnt lgkmcnt(0)
	v_pk_add_f32 v[132:133], v[132:133], v[134:135]
	ds_bpermute_b32 v135, v161, v133
	ds_bpermute_b32 v134, v161, v132
	s_waitcnt lgkmcnt(0)
	v_pk_add_f32 v[132:133], v[132:133], v[134:135]
	ds_bpermute_b32 v135, v171, v133
	ds_bpermute_b32 v134, v171, v132
	s_waitcnt lgkmcnt(0)
	v_pk_add_f32 v[132:133], v[132:133], v[134:135]
	v_mov_b64_e32 v[134:135], s[0:1]
	v_pk_fma_f32 v[132:133], v[132:133], s[36:37], v[134:135] op_sel_hi:[1,0,0]
	s_nop 0
	v_mul_f32_e32 v136, 0x4b800000, v133
	v_cmp_gt_f32_e64 s[0:1], s24, v133
	v_cmp_gt_f32_e32 vcc, s24, v132
	s_nop 0
	v_cndmask_b32_e64 v133, v133, v136, s[0:1]
	v_rsq_f32_e32 v133, v133
	s_nop 0
	v_mul_f32_e32 v136, 0x45800000, v133
	v_cndmask_b32_e64 v178, v133, v136, s[0:1]
	v_mul_f32_e32 v133, 0x4b800000, v132
	v_cndmask_b32_e32 v132, v132, v133, vcc
	v_rsq_f32_e32 v132, v132
	v_mov_b32_e32 v136, v167
	v_mov_b32_e32 v167, v162
	v_pk_mul_f32 v[126:127], v[126:127], v[178:179] op_sel_hi:[1,0]
	v_mul_f32_e32 v133, 0x45800000, v132
	v_cndmask_b32_e32 v158, v132, v133, vcc
	v_mov_b32_e32 v132, v164
	v_mov_b32_e32 v133, v140
	v_mov_b32_e32 v140, v165
	v_pk_add_f32 v[132:133], v[132:133], v[140:141]
	v_pk_mul_f32 v[128:129], v[128:129], v[178:179] op_sel_hi:[1,0]
	v_pk_add_f32 v[132:133], v[136:137], v[132:133]
	v_pk_mul_f32 v[122:123], v[122:123], v[158:159] op_sel_hi:[1,0]
	v_pk_add_f32 v[132:133], v[166:167], v[132:133]
	ds_bpermute_b32 v137, v149, v133
	ds_bpermute_b32 v136, v149, v132
	v_pk_mul_f32 v[124:125], v[124:125], v[158:159] op_sel_hi:[1,0]
	v_pk_mul_f32 v[110:111], v[110:111], v[158:159] op_sel_hi:[1,0]
	v_pk_mul_f32 v[112:113], v[112:113], v[158:159] op_sel_hi:[1,0]
	v_pk_mul_f32 v[80:81], v[80:81], v[158:159] op_sel_hi:[1,0]
	s_waitcnt lgkmcnt(0)
	v_pk_add_f32 v[132:133], v[132:133], v[136:137]
	ds_bpermute_b32 v137, v151, v133
	ds_bpermute_b32 v136, v151, v132
	v_pk_mul_f32 v[82:83], v[82:83], v[158:159] op_sel_hi:[1,0]
	v_pk_mul_f32 v[8:9], v[8:9], v[158:159] op_sel_hi:[1,0]
	v_pk_mul_f32 v[10:11], v[10:11], v[158:159] op_sel_hi:[1,0]
	s_waitcnt lgkmcnt(0)
	v_pk_add_f32 v[132:133], v[132:133], v[136:137]
	ds_bpermute_b32 v137, v153, v133
	ds_bpermute_b32 v136, v153, v132
	s_waitcnt lgkmcnt(0)
	v_pk_add_f32 v[132:133], v[132:133], v[136:137]
	ds_bpermute_b32 v137, v159, v133
	ds_bpermute_b32 v136, v159, v132
	s_waitcnt lgkmcnt(0)
	v_pk_add_f32 v[132:133], v[132:133], v[136:137]
	ds_bpermute_b32 v137, v161, v133
	ds_bpermute_b32 v136, v161, v132
	s_waitcnt lgkmcnt(0)
	v_pk_add_f32 v[132:133], v[132:133], v[136:137]
	ds_bpermute_b32 v137, v171, v133
	ds_bpermute_b32 v136, v171, v132
	s_waitcnt lgkmcnt(0)
	v_pk_add_f32 v[132:133], v[132:133], v[136:137]
	s_nop 0
	v_pk_fma_f32 v[132:133], v[132:133], s[36:37], v[134:135] op_sel_hi:[1,0,0]
	s_nop 0
	v_mul_f32_e32 v134, 0x4b800000, v133
	v_cmp_gt_f32_e64 s[0:1], s24, v133
	v_cmp_gt_f32_e32 vcc, s24, v132
	s_nop 0
	v_cndmask_b32_e64 v133, v133, v134, s[0:1]
	v_rsq_f32_e32 v133, v133
	s_nop 0
	v_mul_f32_e32 v134, 0x45800000, v133
	v_cndmask_b32_e64 v174, v133, v134, s[0:1]
	v_mul_f32_e32 v133, 0x4b800000, v132
	v_cndmask_b32_e32 v132, v132, v133, vcc
	v_rsq_f32_e32 v132, v132
	v_pk_mul_f32 v[114:115], v[114:115], v[174:175] op_sel_hi:[1,0]
	v_pk_mul_f32 v[116:117], v[116:117], v[174:175] op_sel_hi:[1,0]
	v_pk_mul_f32 v[92:93], v[92:93], v[174:175] op_sel_hi:[1,0]
	v_mul_f32_e32 v133, 0x45800000, v132
	v_cndmask_b32_e32 v160, v132, v133, vcc
	v_lshl_add_u64 v[132:133], v[156:157], 0, v[96:97]
	v_mov_b64_e32 v[232:233], v[132:133]
	global_load_dwordx4 v[134:137], v[144:145], off
	global_load_dwordx4 v[138:141], v[132:133], off
	s_nop 0
	global_load_dwordx4 v[130:133], v[180:181], off
	global_load_dwordx4 v[184:187], v[144:145], off offset:1024
	global_load_dwordx4 v[188:191], v[232:233], off offset:1024
	global_load_dwordx4 v[192:195], v[180:181], off offset:1024
	global_load_dwordx4 v[196:199], v[144:145], off offset:2048
	global_load_dwordx4 v[200:203], v[232:233], off offset:2048
	global_load_dwordx4 v[216:219], v[180:181], off offset:2048
	global_load_dwordx4 v[220:223], v[144:145], off offset:3072
	global_load_dwordx4 v[224:227], v[232:233], off offset:3072
	global_load_dwordx4 v[228:231], v[180:181], off offset:3072
	v_pk_mul_f32 v[106:107], v[106:107], v[160:161] op_sel_hi:[1,0]
	v_pk_mul_f32 v[108:109], v[108:109], v[160:161] op_sel_hi:[1,0]
	v_lshlrev_b32_e32 v96, 2, v148
	v_pk_mul_f32 v[94:95], v[94:95], v[174:175] op_sel_hi:[1,0]
	v_pk_mul_f32 v[64:65], v[64:65], v[160:161] op_sel_hi:[1,0]
	v_pk_mul_f32 v[66:67], v[66:67], v[160:161] op_sel_hi:[1,0]
	v_pk_mul_f32 v[40:41], v[40:41], v[174:175] op_sel_hi:[1,0]
	v_pk_mul_f32 v[42:43], v[42:43], v[174:175] op_sel_hi:[1,0]
	v_pk_mul_f32 v[16:17], v[16:17], v[160:161] op_sel_hi:[1,0]
	v_pk_mul_f32 v[18:19], v[18:19], v[160:161] op_sel_hi:[1,0]
	v_pk_mul_f32 v[4:5], v[4:5], v[174:175] op_sel_hi:[1,0]
	v_pk_mul_f32 v[6:7], v[6:7], v[174:175] op_sel_hi:[1,0]
	v_pk_mul_f32 v[0:1], v[0:1], v[160:161] op_sel_hi:[1,0]
	v_pk_mul_f32 v[2:3], v[2:3], v[160:161] op_sel_hi:[1,0]
	s_waitcnt vmcnt(10)
	v_pk_add_f32 v[138:139], v[138:139], 1.0 op_sel_hi:[1,0]
	s_nop 0
	v_pk_mul_f32 v[134:135], v[134:135], v[138:139]
	v_pk_add_f32 v[138:139], v[140:141], 1.0 op_sel_hi:[1,0]
	s_waitcnt vmcnt(9)
	v_pk_fma_f32 v[126:127], v[126:127], v[134:135], v[130:131]
	v_pk_mul_f32 v[136:137], v[136:137], v[138:139]
	v_pk_fma_f32 v[122:123], v[134:135], v[122:123], v[130:131]
	v_pk_fma_f32 v[128:129], v[128:129], v[136:137], v[132:133]
	v_pk_fma_f32 v[124:125], v[124:125], v[136:137], v[132:133]
	v_pk_fma_f32 v[114:115], v[134:135], v[114:115], v[130:131]
	v_pk_fma_f32 v[116:117], v[136:137], v[116:117], v[132:133]
	v_cvt_pk_bf16_f32 v126, v126, v127
	v_cvt_pk_bf16_f32 v127, v128, v129
	v_lshlrev_b64 v[128:129], 11, v[176:177]
	v_cvt_pk_bf16_f32 v122, v122, v123
	v_cvt_pk_bf16_f32 v123, v124, v125
	v_add_u32_e32 v124, -2, v154
	v_cvt_pk_bf16_f32 v114, v114, v115
	v_cvt_pk_bf16_f32 v115, v116, v117
	v_add_u32_e32 v116, -1, v154
	v_lshl_add_u64 v[138:139], v[146:147], 0, v[128:129]
	v_ashrrev_i32_e32 v125, 31, v124
	v_ashrrev_i32_e32 v117, 31, v116
	global_store_dwordx2 v[138:139], v[126:127], off
	v_lshlrev_b64 v[126:127], 11, v[124:125]
	v_lshlrev_b64 v[138:139], 11, v[116:117]
	v_pk_fma_f32 v[106:107], v[134:135], v[106:107], v[130:131]
	v_pk_fma_f32 v[108:109], v[136:137], v[108:109], v[132:133]
	v_lshlrev_b64 v[130:131], 11, v[154:155]
	v_lshl_add_u64 v[124:125], v[146:147], 0, v[126:127]
	v_lshl_add_u64 v[116:117], v[146:147], 0, v[138:139]
	v_cvt_pk_bf16_f32 v106, v106, v107
	v_cvt_pk_bf16_f32 v107, v108, v109
	v_lshl_add_u64 v[108:109], v[146:147], 0, v[130:131]
	global_store_dwordx2 v[124:125], v[122:123], off
	global_store_dwordx2 v[116:117], v[114:115], off
	global_store_dwordx2 v[108:109], v[106:107], off
	v_lshl_add_u64 v[114:115], v[156:157], 0, v[96:97]
	s_nop 0
	s_nop 0
	v_lshlrev_b32_e32 v96, 1, v148
	v_mov_b32_e32 v154, v175
	s_waitcnt vmcnt(11)
	v_pk_add_f32 v[114:115], v[188:189], 1.0 op_sel_hi:[1, 0]
	v_pk_add_f32 v[116:117], v[190:191], 1.0 op_sel_hi:[1, 0]
	v_pk_mul_f32 v[106:107], v[184:185], v[114:115]
	v_pk_mul_f32 v[114:115], v[118:119], v[178:179] op_sel_hi:[1,0]
	v_pk_mul_f32 v[108:109], v[186:187], v[116:117]
	v_pk_mul_f32 v[116:117], v[120:121], v[178:179] op_sel_hi:[1,0]
	s_waitcnt vmcnt(10)
	v_pk_fma_f32 v[114:115], v[114:115], v[106:107], v[192:193]
	v_pk_fma_f32 v[116:117], v[116:117], v[108:109], v[194:195]
	v_cvt_pk_bf16_f32 v114, v114, v115
	v_cvt_pk_bf16_f32 v115, v116, v117
	v_lshl_add_u64 v[116:117], s[22:23], 0, v[128:129]
	v_pk_fma_f32 v[110:111], v[110:111], v[106:107], v[192:193]
	v_pk_fma_f32 v[112:113], v[112:113], v[108:109], v[194:195]
	v_lshl_add_u64 v[118:119], v[116:117], 0, v[96:97]
	v_cvt_pk_bf16_f32 v110, v110, v111
	v_cvt_pk_bf16_f32 v111, v112, v113
	v_lshl_add_u64 v[112:113], s[22:23], 0, v[126:127]
	global_store_dwordx2 v[118:119], v[114:115], off
	v_lshl_add_u64 v[114:115], v[112:113], 0, v[96:97]
	global_store_dwordx2 v[114:115], v[110:111], off
	v_pk_fma_f32 v[92:93], v[92:93], v[106:107], v[192:193]
	v_pk_fma_f32 v[94:95], v[94:95], v[108:109], v[194:195]
	v_lshl_add_u64 v[110:111], s[22:23], 0, v[138:139]
	v_pk_fma_f32 v[64:65], v[64:65], v[106:107], v[192:193]
	v_pk_fma_f32 v[66:67], v[66:67], v[108:109], v[194:195]
	v_lshl_add_u64 v[114:115], s[22:23], 0, v[130:131]
	v_cvt_pk_bf16_f32 v92, v92, v93
	v_cvt_pk_bf16_f32 v93, v94, v95
	v_lshl_add_u64 v[94:95], v[110:111], 0, v[96:97]
	v_cvt_pk_bf16_f32 v64, v64, v65
	v_cvt_pk_bf16_f32 v65, v66, v67
	v_lshl_add_u64 v[66:67], v[114:115], 0, v[96:97]
	v_lshlrev_b32_e32 v96, 2, v150
	global_store_dwordx2 v[94:95], v[92:93], off
	global_store_dwordx2 v[66:67], v[64:65], off
	v_lshl_add_u64 v[92:93], v[156:157], 0, v[96:97]
	s_nop 0
	s_nop 0
	v_lshlrev_b32_e32 v96, 1, v150
	v_mov_b64_e32 v[128:129], v[14:15]
	v_mov_b64_e32 v[126:127], v[12:13]
	v_mov_b64_e32 v[124:125], v[90:91]
	v_mov_b64_e32 v[122:123], v[88:89]
	v_mov_b64_e32 v[120:121], v[22:23]
	v_mov_b64_e32 v[118:119], v[20:21]
	s_waitcnt vmcnt(12)
	v_pk_add_f32 v[92:93], v[200:201], 1.0 op_sel_hi:[1, 0]
	v_pk_add_f32 v[94:95], v[202:203], 1.0 op_sel_hi:[1, 0]
	v_pk_mul_f32 v[64:65], v[196:197], v[92:93]
	v_pk_mul_f32 v[92:93], v[98:99], v[178:179] op_sel_hi:[1,0]
	v_pk_mul_f32 v[66:67], v[198:199], v[94:95]
	v_pk_mul_f32 v[94:95], v[100:101], v[178:179] op_sel_hi:[1,0]
	s_waitcnt vmcnt(11)
	v_pk_fma_f32 v[92:93], v[92:93], v[64:65], v[216:217]
	v_pk_fma_f32 v[94:95], v[94:95], v[66:67], v[218:219]
	v_pk_fma_f32 v[80:81], v[80:81], v[64:65], v[216:217]
	v_pk_fma_f32 v[82:83], v[82:83], v[66:67], v[218:219]
	v_pk_fma_f32 v[40:41], v[40:41], v[64:65], v[216:217]
	v_pk_fma_f32 v[42:43], v[42:43], v[66:67], v[218:219]
	v_pk_fma_f32 v[16:17], v[16:17], v[64:65], v[216:217]
	v_pk_fma_f32 v[18:19], v[18:19], v[66:67], v[218:219]
	v_cvt_pk_bf16_f32 v92, v92, v93
	v_cvt_pk_bf16_f32 v93, v94, v95
	v_lshl_add_u64 v[94:95], v[116:117], 0, v[96:97]
	v_cvt_pk_bf16_f32 v80, v80, v81
	v_cvt_pk_bf16_f32 v81, v82, v83
	v_lshl_add_u64 v[82:83], v[112:113], 0, v[96:97]
	v_cvt_pk_bf16_f32 v40, v40, v41
	v_cvt_pk_bf16_f32 v41, v42, v43
	v_lshl_add_u64 v[42:43], v[110:111], 0, v[96:97]
	v_cvt_pk_bf16_f32 v16, v16, v17
	v_cvt_pk_bf16_f32 v17, v18, v19
	v_lshl_add_u64 v[18:19], v[114:115], 0, v[96:97]
	v_lshlrev_b32_e32 v96, 2, v152
	global_store_dwordx2 v[94:95], v[92:93], off
	global_store_dwordx2 v[82:83], v[80:81], off
	global_store_dwordx2 v[42:43], v[40:41], off
	global_store_dwordx2 v[18:19], v[16:17], off
	v_lshl_add_u64 v[40:41], v[156:157], 0, v[96:97]
	s_nop 0
	s_nop 0
	v_lshlrev_b32_e32 v96, 1, v152
	v_mov_b64_e32 v[108:109], v[70:71]
	v_mov_b64_e32 v[106:107], v[68:69]
	v_mov_b64_e32 v[94:95], v[50:51]
	v_mov_b64_e32 v[92:93], v[48:49]
	v_mov_b64_e32 v[100:101], v[26:27]
	v_mov_b64_e32 v[98:99], v[24:25]
	v_mov_b64_e32 v[82:83], v[38:39]
	v_mov_b64_e32 v[80:81], v[36:37]
	s_waitcnt vmcnt(13)
	v_pk_add_f32 v[40:41], v[224:225], 1.0 op_sel_hi:[1, 0]
	v_pk_add_f32 v[42:43], v[226:227], 1.0 op_sel_hi:[1, 0]
	v_pk_mul_f32 v[16:17], v[220:221], v[40:41]
	v_pk_mul_f32 v[40:41], v[52:53], v[178:179] op_sel_hi:[1,0]
	v_pk_mul_f32 v[18:19], v[222:223], v[42:43]
	v_pk_mul_f32 v[42:43], v[54:55], v[178:179] op_sel_hi:[1,0]
	s_waitcnt vmcnt(12)
	v_pk_fma_f32 v[40:41], v[40:41], v[16:17], v[228:229]
	v_pk_fma_f32 v[42:43], v[42:43], v[18:19], v[230:231]
	v_pk_fma_f32 v[8:9], v[8:9], v[16:17], v[228:229]
	v_pk_fma_f32 v[10:11], v[10:11], v[18:19], v[230:231]
	v_pk_fma_f32 v[4:5], v[4:5], v[16:17], v[228:229]
	v_pk_fma_f32 v[6:7], v[6:7], v[18:19], v[230:231]
	v_pk_fma_f32 v[0:1], v[0:1], v[16:17], v[228:229]
	v_pk_fma_f32 v[2:3], v[2:3], v[18:19], v[230:231]
	v_cvt_pk_bf16_f32 v40, v40, v41
	v_cvt_pk_bf16_f32 v41, v42, v43
	v_lshl_add_u64 v[42:43], v[116:117], 0, v[96:97]
	v_cvt_pk_bf16_f32 v8, v8, v9
	v_cvt_pk_bf16_f32 v9, v10, v11
	v_lshl_add_u64 v[10:11], v[112:113], 0, v[96:97]
	v_cvt_pk_bf16_f32 v4, v4, v5
	v_cvt_pk_bf16_f32 v5, v6, v7
	v_lshl_add_u64 v[6:7], v[110:111], 0, v[96:97]
	v_cvt_pk_bf16_f32 v0, v0, v1
	v_cvt_pk_bf16_f32 v1, v2, v3
	v_lshl_add_u64 v[2:3], v[114:115], 0, v[96:97]
	global_store_dwordx2 v[42:43], v[40:41], off
	global_store_dwordx2 v[10:11], v[8:9], off
	global_store_dwordx2 v[6:7], v[4:5], off
	global_store_dwordx2 v[2:3], v[0:1], off
	v_mov_b64_e32 v[116:117], v[46:47]
	v_mov_b64_e32 v[114:115], v[44:45]
	v_mov_b64_e32 v[112:113], v[34:35]
	v_mov_b64_e32 v[110:111], v[32:33]
	v_mov_b64_e32 v[66:67], v[74:75]
	v_mov_b64_e32 v[64:65], v[72:73]
	v_mov_b64_e32 v[42:43], v[58:59]
	v_mov_b64_e32 v[40:41], v[56:57]
	v_mov_b64_e32 v[18:19], v[86:87]
	v_mov_b64_e32 v[16:17], v[84:85]
	v_mov_b64_e32 v[54:55], v[30:31]
	v_mov_b64_e32 v[52:53], v[28:29]
	v_mov_b64_e32 v[10:11], v[78:79]
	v_mov_b64_e32 v[8:9], v[76:77]
	v_mov_b64_e32 v[6:7], v[62:63]
	v_mov_b64_e32 v[4:5], v[60:61]
	v_mov_b64_e32 v[2:3], v[104:105]
	v_mov_b64_e32 v[0:1], v[102:103]
	s_andn2_b64 exec, exec, s[30:31]
	s_cbranch_execz .LBB0_88

.LBB0_456:
	s_or_b64 exec, exec, s[46:47]
	v_add_u32_e32 v130, 0xffffdffd, v154
	v_lshrrev_b32_e32 v130, 11, v130
	s_and_b64 s[0:1], exec, s[0:1]
	v_add_u32_e32 v130, 1, v130
	s_or_b64 s[30:31], s[0:1], s[30:31]
	v_readlane_b32 s0, v252, 40
	v_cndmask_b32_e32 v130, 0, v130, vcc
	v_readlane_b32 s1, v252, 41
	v_add_u32_e32 v132, s3, v130
	s_waitcnt vmcnt(0)
	v_mov_b32_e32 v133, v126
	v_mov_b64_e32 v[130:131], s[0:1]
	s_mov_b32 s0, 0x9000
	v_mad_u64_u32 v[130:131], s[0:1], v132, s0, v[130:131]
	v_mov_b32_e32 v132, v118
	v_pk_mul_f32 v[132:133], v[132:133], v[132:133]
	v_mov_b32_e32 v134, v119
	v_mov_b32_e32 v135, v127
	v_pk_fma_f32 v[132:133], v[134:135], v[134:135], v[132:133]
	v_mov_b32_e32 v134, v120
	v_mov_b32_e32 v135, v128
	v_pk_fma_f32 v[132:133], v[134:135], v[134:135], v[132:133]
	v_mov_b32_e32 v134, v121
	v_mov_b32_e32 v135, v129
	v_pk_fma_f32 v[132:133], v[134:135], v[134:135], v[132:133]
	v_mov_b32_e32 v134, v52
	v_mov_b32_e32 v135, v98
	v_pk_mul_f32 v[134:135], v[134:135], v[134:135]
	v_mov_b32_e32 v136, v53
	v_mov_b32_e32 v137, v99
	v_pk_fma_f32 v[134:135], v[136:137], v[136:137], v[134:135]
	v_mov_b32_e32 v136, v54
	v_mov_b32_e32 v137, v100
	v_pk_fma_f32 v[134:135], v[136:137], v[136:137], v[134:135]
	v_mov_b32_e32 v136, v55
	v_mov_b32_e32 v137, v101
	v_pk_fma_f32 v[134:135], v[136:137], v[136:137], v[134:135]
	v_mov_b32_e32 v136, v110
	v_mov_b32_e32 v137, v122
	v_pk_mul_f32 v[136:137], v[136:137], v[136:137]
	v_mov_b32_e32 v138, v111
	v_mov_b32_e32 v139, v123
	v_pk_fma_f32 v[136:137], v[138:139], v[138:139], v[136:137]
	v_mov_b32_e32 v138, v112
	v_mov_b32_e32 v139, v124
	v_pk_fma_f32 v[136:137], v[138:139], v[138:139], v[136:137]
	v_mov_b32_e32 v138, v113
	v_mov_b32_e32 v139, v125
	v_pk_fma_f32 v[136:137], v[138:139], v[138:139], v[136:137]
	v_mov_b32_e32 v138, v8
	v_mov_b32_e32 v139, v80
	v_pk_mul_f32 v[138:139], v[138:139], v[138:139]
	v_mov_b32_e32 v140, v9
	v_mov_b32_e32 v141, v81
	v_pk_fma_f32 v[138:139], v[140:141], v[140:141], v[138:139]
	v_mov_b32_e32 v140, v10
	v_mov_b32_e32 v141, v82
	v_pk_fma_f32 v[138:139], v[140:141], v[140:141], v[138:139]
	v_mov_b32_e32 v140, v11
	v_mov_b32_e32 v141, v83
	v_pk_fma_f32 v[138:139], v[140:141], v[140:141], v[138:139]
	v_mov_b32_e32 v140, v92
	v_mov_b32_e32 v141, v114
	v_pk_mul_f32 v[140:141], v[140:141], v[140:141]
	v_mov_b32_e32 v162, v93
	v_mov_b32_e32 v163, v115
	v_pk_fma_f32 v[140:141], v[162:163], v[162:163], v[140:141]
	v_mov_b32_e32 v162, v94
	v_mov_b32_e32 v163, v116
	v_pk_fma_f32 v[140:141], v[162:163], v[162:163], v[140:141]
	v_mov_b32_e32 v162, v95
	v_mov_b32_e32 v163, v117
	v_pk_fma_f32 v[140:141], v[162:163], v[162:163], v[140:141]
	v_mov_b32_e32 v162, v4
	v_mov_b32_e32 v163, v40
	v_pk_mul_f32 v[162:163], v[162:163], v[162:163]
	v_mov_b32_e32 v166, v5
	v_mov_b32_e32 v167, v41
	v_pk_fma_f32 v[162:163], v[166:167], v[166:167], v[162:163]
	v_mov_b32_e32 v166, v6
	v_mov_b32_e32 v167, v42
	v_pk_fma_f32 v[162:163], v[166:167], v[166:167], v[162:163]
	v_mov_b32_e32 v166, v7
	v_mov_b32_e32 v167, v43
	v_pk_fma_f32 v[162:163], v[166:167], v[166:167], v[162:163]
	v_mov_b32_e32 v166, v64
	v_mov_b32_e32 v167, v106
	v_pk_mul_f32 v[166:167], v[166:167], v[166:167]
	v_mov_b32_e32 v168, v65
	v_mov_b32_e32 v169, v107
	v_pk_fma_f32 v[166:167], v[168:169], v[168:169], v[166:167]
	v_mov_b32_e32 v168, v66
	v_mov_b32_e32 v169, v108
	v_pk_fma_f32 v[166:167], v[168:169], v[168:169], v[166:167]
	v_mov_b32_e32 v168, v67
	v_mov_b32_e32 v169, v109
	v_pk_fma_f32 v[166:167], v[168:169], v[168:169], v[166:167]
	v_mov_b32_e32 v168, v0
	v_mov_b32_e32 v169, v16
	v_pk_mul_f32 v[168:169], v[168:169], v[168:169]
	v_mov_b32_e32 v178, v1
	v_mov_b32_e32 v179, v17
	v_pk_fma_f32 v[168:169], v[178:179], v[178:179], v[168:169]
	v_mov_b32_e32 v178, v2
	v_mov_b32_e32 v179, v18
	v_pk_fma_f32 v[168:169], v[178:179], v[178:179], v[168:169]
	v_mov_b32_e32 v178, v3
	v_mov_b32_e32 v179, v19
	v_pk_fma_f32 v[168:169], v[178:179], v[178:179], v[168:169]
	v_mov_b32_e32 v178, v136
	v_mov_b32_e32 v179, v132
	v_mov_b32_e32 v132, v137
	v_pk_add_f32 v[132:133], v[178:179], v[132:133]
	v_mov_b32_e32 v136, v139
	v_mov_b32_e32 v137, v135
	v_pk_add_f32 v[132:133], v[136:137], v[132:133]
	v_mov_b32_e32 v139, v134
	v_pk_add_f32 v[132:133], v[138:139], v[132:133]
	ds_bpermute_b32 v135, v149, v133
	ds_bpermute_b32 v134, v149, v132
	s_mov_b64 s[0:1], 0x1000
	v_lshl_add_u64 v[156:157], v[130:131], 0, s[0:1]
	s_mov_b32 s0, 0x358637bd
	s_mov_b32 s36, 0x3a800000
	s_waitcnt lgkmcnt(0)
	v_pk_add_f32 v[132:133], v[132:133], v[134:135]
	ds_bpermute_b32 v135, v151, v133
	ds_bpermute_b32 v134, v151, v132
	s_mov_b32 s24, 0x800000
	v_mov_b32_e32 v137, v163
	v_lshl_add_u64 v[180:181], v[130:131], 0, v[96:97]
	v_add_u32_e32 v176, -3, v154
	s_waitcnt lgkmcnt(0)
	v_pk_add_f32 v[132:133], v[132:133], v[134:135]
	ds_bpermute_b32 v135, v153, v133
	ds_bpermute_b32 v134, v153, v132
	v_ashrrev_i32_e32 v177, 31, v176
	v_ashrrev_i32_e32 v155, 31, v154
	s_mov_b32 s82, 0x800000
	s_waitcnt lgkmcnt(0)
	v_pk_add_f32 v[132:133], v[132:133], v[134:135]
	ds_bpermute_b32 v135, v159, v133
	ds_bpermute_b32 v134, v159, v132
	s_waitcnt lgkmcnt(0)
	v_pk_add_f32 v[132:133], v[132:133], v[134:135]
	ds_bpermute_b32 v135, v161, v133
	ds_bpermute_b32 v134, v161, v132
	s_waitcnt lgkmcnt(0)
	v_pk_add_f32 v[132:133], v[132:133], v[134:135]
	ds_bpermute_b32 v135, v171, v133
	ds_bpermute_b32 v134, v171, v132
	s_waitcnt lgkmcnt(0)
	v_pk_add_f32 v[132:133], v[132:133], v[134:135]
	v_mov_b64_e32 v[134:135], s[0:1]
	v_pk_fma_f32 v[132:133], v[132:133], s[36:37], v[134:135] op_sel_hi:[1,0,0]
	s_nop 0
	v_mul_f32_e32 v136, 0x4b800000, v133
	v_cmp_gt_f32_e64 s[0:1], s24, v133
	v_cmp_gt_f32_e32 vcc, s24, v132
	s_nop 0
	v_cndmask_b32_e64 v133, v133, v136, s[0:1]
	v_rsq_f32_e32 v133, v133
	s_nop 0
	v_mul_f32_e32 v136, 0x45800000, v133
	v_cndmask_b32_e64 v178, v133, v136, s[0:1]
	v_mul_f32_e32 v133, 0x4b800000, v132
	v_cndmask_b32_e32 v132, v132, v133, vcc
	v_rsq_f32_e32 v132, v132
	v_mov_b32_e32 v136, v169
	v_mov_b32_e32 v169, v162
	v_pk_mul_f32 v[126:127], v[126:127], v[178:179] op_sel_hi:[1,0]
	v_mul_f32_e32 v133, 0x45800000, v132
	v_cndmask_b32_e32 v158, v132, v133, vcc
	v_mov_b32_e32 v132, v166
	v_mov_b32_e32 v133, v140
	v_mov_b32_e32 v140, v167
	v_pk_add_f32 v[132:133], v[132:133], v[140:141]
	v_pk_mul_f32 v[128:129], v[128:129], v[178:179] op_sel_hi:[1,0]
	v_pk_add_f32 v[132:133], v[136:137], v[132:133]
	v_pk_mul_f32 v[122:123], v[122:123], v[158:159] op_sel_hi:[1,0]
	v_pk_add_f32 v[132:133], v[168:169], v[132:133]
	ds_bpermute_b32 v137, v149, v133
	ds_bpermute_b32 v136, v149, v132
	v_pk_mul_f32 v[124:125], v[124:125], v[158:159] op_sel_hi:[1,0]
	v_pk_mul_f32 v[110:111], v[110:111], v[158:159] op_sel_hi:[1,0]
	v_pk_mul_f32 v[112:113], v[112:113], v[158:159] op_sel_hi:[1,0]
	v_pk_mul_f32 v[80:81], v[80:81], v[158:159] op_sel_hi:[1,0]
	s_waitcnt lgkmcnt(0)
	v_pk_add_f32 v[132:133], v[132:133], v[136:137]
	ds_bpermute_b32 v137, v151, v133
	ds_bpermute_b32 v136, v151, v132
	v_pk_mul_f32 v[82:83], v[82:83], v[158:159] op_sel_hi:[1,0]
	v_pk_mul_f32 v[8:9], v[8:9], v[158:159] op_sel_hi:[1,0]
	v_pk_mul_f32 v[10:11], v[10:11], v[158:159] op_sel_hi:[1,0]
	s_waitcnt lgkmcnt(0)
	v_pk_add_f32 v[132:133], v[132:133], v[136:137]
	ds_bpermute_b32 v137, v153, v133
	ds_bpermute_b32 v136, v153, v132
	s_waitcnt lgkmcnt(0)
	v_pk_add_f32 v[132:133], v[132:133], v[136:137]
	ds_bpermute_b32 v137, v159, v133
	ds_bpermute_b32 v136, v159, v132
	s_waitcnt lgkmcnt(0)
	v_pk_add_f32 v[132:133], v[132:133], v[136:137]
	ds_bpermute_b32 v137, v161, v133
	ds_bpermute_b32 v136, v161, v132
	s_waitcnt lgkmcnt(0)
	v_pk_add_f32 v[132:133], v[132:133], v[136:137]
	ds_bpermute_b32 v137, v171, v133
	ds_bpermute_b32 v136, v171, v132
	s_waitcnt lgkmcnt(0)
	v_pk_add_f32 v[132:133], v[132:133], v[136:137]
	s_nop 0
	v_pk_fma_f32 v[132:133], v[132:133], s[36:37], v[134:135] op_sel_hi:[1,0,0]
	s_nop 0
	v_mul_f32_e32 v134, 0x4b800000, v133
	v_cmp_gt_f32_e64 s[0:1], s24, v133
	v_cmp_gt_f32_e32 vcc, s24, v132
	s_nop 0
	v_cndmask_b32_e64 v133, v133, v134, s[0:1]
	v_rsq_f32_e32 v133, v133
	s_nop 0
	v_mul_f32_e32 v134, 0x45800000, v133
	v_cndmask_b32_e64 v174, v133, v134, s[0:1]
	v_mul_f32_e32 v133, 0x4b800000, v132
	v_cndmask_b32_e32 v132, v132, v133, vcc
	v_rsq_f32_e32 v132, v132
	v_pk_mul_f32 v[114:115], v[114:115], v[174:175] op_sel_hi:[1,0]
	v_pk_mul_f32 v[116:117], v[116:117], v[174:175] op_sel_hi:[1,0]
	v_pk_mul_f32 v[92:93], v[92:93], v[174:175] op_sel_hi:[1,0]
	v_mul_f32_e32 v133, 0x45800000, v132
	v_cndmask_b32_e32 v160, v132, v133, vcc
	v_lshl_add_u64 v[132:133], v[156:157], 0, v[96:97]
	v_mov_b64_e32 v[232:233], v[132:133]
	global_load_dwordx4 v[134:137], v[144:145], off
	global_load_dwordx4 v[138:141], v[132:133], off
	s_nop 0
	global_load_dwordx4 v[130:133], v[180:181], off
	global_load_dwordx4 v[184:187], v[144:145], off offset:1024
	global_load_dwordx4 v[188:191], v[232:233], off offset:1024
	global_load_dwordx4 v[192:195], v[180:181], off offset:1024
	global_load_dwordx4 v[196:199], v[144:145], off offset:2048
	global_load_dwordx4 v[200:203], v[232:233], off offset:2048
	global_load_dwordx4 v[216:219], v[180:181], off offset:2048
	global_load_dwordx4 v[220:223], v[144:145], off offset:3072
	global_load_dwordx4 v[224:227], v[232:233], off offset:3072
	global_load_dwordx4 v[228:231], v[180:181], off offset:3072
	v_pk_mul_f32 v[106:107], v[106:107], v[160:161] op_sel_hi:[1,0]
	v_pk_mul_f32 v[108:109], v[108:109], v[160:161] op_sel_hi:[1,0]
	v_lshlrev_b32_e32 v96, 2, v148
	v_pk_mul_f32 v[94:95], v[94:95], v[174:175] op_sel_hi:[1,0]
	v_pk_mul_f32 v[64:65], v[64:65], v[160:161] op_sel_hi:[1,0]
	v_pk_mul_f32 v[66:67], v[66:67], v[160:161] op_sel_hi:[1,0]
	v_pk_mul_f32 v[40:41], v[40:41], v[174:175] op_sel_hi:[1,0]
	v_pk_mul_f32 v[42:43], v[42:43], v[174:175] op_sel_hi:[1,0]
	v_pk_mul_f32 v[16:17], v[16:17], v[160:161] op_sel_hi:[1,0]
	v_pk_mul_f32 v[18:19], v[18:19], v[160:161] op_sel_hi:[1,0]
	v_pk_mul_f32 v[4:5], v[4:5], v[174:175] op_sel_hi:[1,0]
	v_pk_mul_f32 v[6:7], v[6:7], v[174:175] op_sel_hi:[1,0]
	v_pk_mul_f32 v[0:1], v[0:1], v[160:161] op_sel_hi:[1,0]
	v_pk_mul_f32 v[2:3], v[2:3], v[160:161] op_sel_hi:[1,0]
	s_waitcnt vmcnt(10)
	v_pk_add_f32 v[138:139], v[138:139], 1.0 op_sel_hi:[1,0]
	s_nop 0
	v_pk_mul_f32 v[134:135], v[134:135], v[138:139]
	v_pk_add_f32 v[138:139], v[140:141], 1.0 op_sel_hi:[1,0]
	s_waitcnt vmcnt(9)
	v_pk_fma_f32 v[126:127], v[126:127], v[134:135], v[130:131]
	v_pk_mul_f32 v[136:137], v[136:137], v[138:139]
	v_pk_fma_f32 v[122:123], v[134:135], v[122:123], v[130:131]
	v_pk_fma_f32 v[128:129], v[128:129], v[136:137], v[132:133]
	v_pk_fma_f32 v[124:125], v[124:125], v[136:137], v[132:133]
	v_pk_fma_f32 v[114:115], v[134:135], v[114:115], v[130:131]
	v_pk_fma_f32 v[116:117], v[136:137], v[116:117], v[132:133]
	v_cvt_pk_bf16_f32 v126, v126, v127
	v_cvt_pk_bf16_f32 v127, v128, v129
	v_lshlrev_b64 v[128:129], 11, v[176:177]
	v_cvt_pk_bf16_f32 v122, v122, v123
	v_cvt_pk_bf16_f32 v123, v124, v125
	v_add_u32_e32 v124, -2, v154
	v_cvt_pk_bf16_f32 v114, v114, v115
	v_cvt_pk_bf16_f32 v115, v116, v117
	v_add_u32_e32 v116, -1, v154
	v_lshl_add_u64 v[138:139], v[146:147], 0, v[128:129]
	v_ashrrev_i32_e32 v125, 31, v124
	v_ashrrev_i32_e32 v117, 31, v116
	global_store_dwordx2 v[138:139], v[126:127], off
	v_lshlrev_b64 v[126:127], 11, v[124:125]
	v_lshlrev_b64 v[138:139], 11, v[116:117]
	v_pk_fma_f32 v[106:107], v[134:135], v[106:107], v[130:131]
	v_pk_fma_f32 v[108:109], v[136:137], v[108:109], v[132:133]
	v_lshlrev_b64 v[130:131], 11, v[154:155]
	v_lshl_add_u64 v[124:125], v[146:147], 0, v[126:127]
	v_lshl_add_u64 v[116:117], v[146:147], 0, v[138:139]
	v_cvt_pk_bf16_f32 v106, v106, v107
	v_cvt_pk_bf16_f32 v107, v108, v109
	v_lshl_add_u64 v[108:109], v[146:147], 0, v[130:131]
	global_store_dwordx2 v[124:125], v[122:123], off
	global_store_dwordx2 v[116:117], v[114:115], off
	global_store_dwordx2 v[108:109], v[106:107], off
	v_lshl_add_u64 v[114:115], v[156:157], 0, v[96:97]
	s_nop 0
	s_nop 0
	v_lshlrev_b32_e32 v96, 1, v148
	v_mov_b32_e32 v154, v175
	s_waitcnt vmcnt(11)
	v_pk_add_f32 v[114:115], v[188:189], 1.0 op_sel_hi:[1, 0]
	v_pk_add_f32 v[116:117], v[190:191], 1.0 op_sel_hi:[1, 0]
	v_pk_mul_f32 v[106:107], v[184:185], v[114:115]
	v_pk_mul_f32 v[114:115], v[118:119], v[178:179] op_sel_hi:[1,0]
	v_pk_mul_f32 v[108:109], v[186:187], v[116:117]
	v_pk_mul_f32 v[116:117], v[120:121], v[178:179] op_sel_hi:[1,0]
	s_waitcnt vmcnt(10)
	v_pk_fma_f32 v[114:115], v[114:115], v[106:107], v[192:193]
	v_pk_fma_f32 v[116:117], v[116:117], v[108:109], v[194:195]
	v_cvt_pk_bf16_f32 v114, v114, v115
	v_cvt_pk_bf16_f32 v115, v116, v117
	v_lshl_add_u64 v[116:117], s[22:23], 0, v[128:129]
	v_pk_fma_f32 v[110:111], v[110:111], v[106:107], v[192:193]
	v_pk_fma_f32 v[112:113], v[112:113], v[108:109], v[194:195]
	v_lshl_add_u64 v[118:119], v[116:117], 0, v[96:97]
	v_cvt_pk_bf16_f32 v110, v110, v111
	v_cvt_pk_bf16_f32 v111, v112, v113
	v_lshl_add_u64 v[112:113], s[22:23], 0, v[126:127]
	global_store_dwordx2 v[118:119], v[114:115], off
	v_lshl_add_u64 v[114:115], v[112:113], 0, v[96:97]
	global_store_dwordx2 v[114:115], v[110:111], off
	v_pk_fma_f32 v[92:93], v[92:93], v[106:107], v[192:193]
	v_pk_fma_f32 v[94:95], v[94:95], v[108:109], v[194:195]
	v_lshl_add_u64 v[110:111], s[22:23], 0, v[138:139]
	v_pk_fma_f32 v[64:65], v[64:65], v[106:107], v[192:193]
	v_pk_fma_f32 v[66:67], v[66:67], v[108:109], v[194:195]
	v_lshl_add_u64 v[114:115], s[22:23], 0, v[130:131]
	v_cvt_pk_bf16_f32 v92, v92, v93
	v_cvt_pk_bf16_f32 v93, v94, v95
	v_lshl_add_u64 v[94:95], v[110:111], 0, v[96:97]
	v_cvt_pk_bf16_f32 v64, v64, v65
	v_cvt_pk_bf16_f32 v65, v66, v67
	v_lshl_add_u64 v[66:67], v[114:115], 0, v[96:97]
	v_lshlrev_b32_e32 v96, 2, v150
	global_store_dwordx2 v[94:95], v[92:93], off
	global_store_dwordx2 v[66:67], v[64:65], off
	v_lshl_add_u64 v[92:93], v[156:157], 0, v[96:97]
	s_nop 0
	s_nop 0
	v_lshlrev_b32_e32 v96, 1, v150
	v_mov_b64_e32 v[128:129], v[14:15]
	v_mov_b64_e32 v[126:127], v[12:13]
	v_mov_b64_e32 v[124:125], v[90:91]
	v_mov_b64_e32 v[122:123], v[88:89]
	v_mov_b64_e32 v[120:121], v[22:23]
	v_mov_b64_e32 v[118:119], v[20:21]
	s_waitcnt vmcnt(12)
	v_pk_add_f32 v[92:93], v[200:201], 1.0 op_sel_hi:[1, 0]
	v_pk_add_f32 v[94:95], v[202:203], 1.0 op_sel_hi:[1, 0]
	v_pk_mul_f32 v[64:65], v[196:197], v[92:93]
	v_pk_mul_f32 v[92:93], v[98:99], v[178:179] op_sel_hi:[1,0]
	v_pk_mul_f32 v[66:67], v[198:199], v[94:95]
	v_pk_mul_f32 v[94:95], v[100:101], v[178:179] op_sel_hi:[1,0]
	s_waitcnt vmcnt(11)
	v_pk_fma_f32 v[92:93], v[92:93], v[64:65], v[216:217]
	v_pk_fma_f32 v[94:95], v[94:95], v[66:67], v[218:219]
	v_pk_fma_f32 v[80:81], v[80:81], v[64:65], v[216:217]
	v_pk_fma_f32 v[82:83], v[82:83], v[66:67], v[218:219]
	v_pk_fma_f32 v[40:41], v[40:41], v[64:65], v[216:217]
	v_pk_fma_f32 v[42:43], v[42:43], v[66:67], v[218:219]
	v_pk_fma_f32 v[16:17], v[16:17], v[64:65], v[216:217]
	v_pk_fma_f32 v[18:19], v[18:19], v[66:67], v[218:219]
	v_cvt_pk_bf16_f32 v92, v92, v93
	v_cvt_pk_bf16_f32 v93, v94, v95
	v_lshl_add_u64 v[94:95], v[116:117], 0, v[96:97]
	v_cvt_pk_bf16_f32 v80, v80, v81
	v_cvt_pk_bf16_f32 v81, v82, v83
	v_lshl_add_u64 v[82:83], v[112:113], 0, v[96:97]
	v_cvt_pk_bf16_f32 v40, v40, v41
	v_cvt_pk_bf16_f32 v41, v42, v43
	v_lshl_add_u64 v[42:43], v[110:111], 0, v[96:97]
	v_cvt_pk_bf16_f32 v16, v16, v17
	v_cvt_pk_bf16_f32 v17, v18, v19
	v_lshl_add_u64 v[18:19], v[114:115], 0, v[96:97]
	v_lshlrev_b32_e32 v96, 2, v152
	global_store_dwordx2 v[94:95], v[92:93], off
	global_store_dwordx2 v[82:83], v[80:81], off
	global_store_dwordx2 v[42:43], v[40:41], off
	global_store_dwordx2 v[18:19], v[16:17], off
	v_lshl_add_u64 v[40:41], v[156:157], 0, v[96:97]
	s_nop 0
	s_nop 0
	v_lshlrev_b32_e32 v96, 1, v152
	v_mov_b64_e32 v[108:109], v[70:71]
	v_mov_b64_e32 v[106:107], v[68:69]
	v_mov_b64_e32 v[94:95], v[50:51]
	v_mov_b64_e32 v[92:93], v[48:49]
	v_mov_b64_e32 v[100:101], v[26:27]
	v_mov_b64_e32 v[98:99], v[24:25]
	v_mov_b64_e32 v[82:83], v[38:39]
	v_mov_b64_e32 v[80:81], v[36:37]
	s_waitcnt vmcnt(13)
	v_pk_add_f32 v[40:41], v[224:225], 1.0 op_sel_hi:[1, 0]
	v_pk_add_f32 v[42:43], v[226:227], 1.0 op_sel_hi:[1, 0]
	v_pk_mul_f32 v[16:17], v[220:221], v[40:41]
	v_pk_mul_f32 v[40:41], v[52:53], v[178:179] op_sel_hi:[1,0]
	v_pk_mul_f32 v[18:19], v[222:223], v[42:43]
	v_pk_mul_f32 v[42:43], v[54:55], v[178:179] op_sel_hi:[1,0]
	s_waitcnt vmcnt(12)
	v_pk_fma_f32 v[40:41], v[40:41], v[16:17], v[228:229]
	v_pk_fma_f32 v[42:43], v[42:43], v[18:19], v[230:231]
	v_pk_fma_f32 v[8:9], v[8:9], v[16:17], v[228:229]
	v_pk_fma_f32 v[10:11], v[10:11], v[18:19], v[230:231]
	v_pk_fma_f32 v[4:5], v[4:5], v[16:17], v[228:229]
	v_pk_fma_f32 v[6:7], v[6:7], v[18:19], v[230:231]
	v_pk_fma_f32 v[0:1], v[0:1], v[16:17], v[228:229]
	v_pk_fma_f32 v[2:3], v[2:3], v[18:19], v[230:231]
	v_cvt_pk_bf16_f32 v40, v40, v41
	v_cvt_pk_bf16_f32 v41, v42, v43
	v_lshl_add_u64 v[42:43], v[116:117], 0, v[96:97]
	v_cvt_pk_bf16_f32 v8, v8, v9
	v_cvt_pk_bf16_f32 v9, v10, v11
	v_lshl_add_u64 v[10:11], v[112:113], 0, v[96:97]
	v_cvt_pk_bf16_f32 v4, v4, v5
	v_cvt_pk_bf16_f32 v5, v6, v7
	v_lshl_add_u64 v[6:7], v[110:111], 0, v[96:97]
	v_cvt_pk_bf16_f32 v0, v0, v1
	v_cvt_pk_bf16_f32 v1, v2, v3
	v_lshl_add_u64 v[2:3], v[114:115], 0, v[96:97]
	global_store_dwordx2 v[42:43], v[40:41], off
	global_store_dwordx2 v[10:11], v[8:9], off
	global_store_dwordx2 v[6:7], v[4:5], off
	global_store_dwordx2 v[2:3], v[0:1], off
	v_mov_b64_e32 v[116:117], v[46:47]
	v_mov_b64_e32 v[114:115], v[44:45]
	v_mov_b64_e32 v[112:113], v[34:35]
	v_mov_b64_e32 v[110:111], v[32:33]
	v_mov_b64_e32 v[66:67], v[74:75]
	v_mov_b64_e32 v[64:65], v[72:73]
	v_mov_b64_e32 v[42:43], v[58:59]
	v_mov_b64_e32 v[40:41], v[56:57]
	v_mov_b64_e32 v[18:19], v[86:87]
	v_mov_b64_e32 v[16:17], v[84:85]
	v_mov_b64_e32 v[54:55], v[30:31]
	v_mov_b64_e32 v[52:53], v[28:29]
	v_mov_b64_e32 v[10:11], v[78:79]
	v_mov_b64_e32 v[8:9], v[76:77]
	v_mov_b64_e32 v[6:7], v[62:63]
	v_mov_b64_e32 v[4:5], v[60:61]
	v_mov_b64_e32 v[2:3], v[104:105]
	v_mov_b64_e32 v[0:1], v[102:103]
	s_andn2_b64 exec, exec, s[30:31]
	s_cbranch_execz .LBB0_461

.LBB0_543:
	s_or_b64 exec, exec, s[46:47]
	s_waitcnt vmcnt(0)
	v_mov_b32_e32 v132, v110
	v_mov_b32_e32 v133, v126
	v_pk_mul_f32 v[132:133], v[132:133], v[132:133]
	v_mov_b32_e32 v134, v111
	v_mov_b32_e32 v135, v127
	v_pk_fma_f32 v[132:133], v[134:135], v[134:135], v[132:133]
	v_mov_b32_e32 v134, v112
	v_mov_b32_e32 v135, v128
	v_pk_fma_f32 v[132:133], v[134:135], v[134:135], v[132:133]
	v_mov_b32_e32 v134, v113
	v_mov_b32_e32 v135, v129
	v_pk_fma_f32 v[132:133], v[134:135], v[134:135], v[132:133]
	v_mov_b32_e32 v134, v20
	v_mov_b32_e32 v135, v52
	v_pk_mul_f32 v[134:135], v[134:135], v[134:135]
	v_mov_b32_e32 v136, v21
	v_mov_b32_e32 v137, v53
	v_pk_fma_f32 v[134:135], v[136:137], v[136:137], v[134:135]
	v_mov_b32_e32 v136, v22
	v_mov_b32_e32 v137, v54
	v_pk_fma_f32 v[134:135], v[136:137], v[136:137], v[134:135]
	v_mov_b32_e32 v136, v23
	v_mov_b32_e32 v137, v55
	v_pk_fma_f32 v[134:135], v[136:137], v[136:137], v[134:135]
	v_mov_b32_e32 v136, v72
	v_mov_b32_e32 v137, v122
	v_pk_mul_f32 v[136:137], v[136:137], v[136:137]
	v_mov_b32_e32 v138, v73
	v_mov_b32_e32 v139, v123
	v_pk_fma_f32 v[136:137], v[138:139], v[138:139], v[136:137]
	v_mov_b32_e32 v138, v74
	v_mov_b32_e32 v139, v124
	v_pk_fma_f32 v[136:137], v[138:139], v[138:139], v[136:137]
	v_mov_b32_e32 v138, v75
	v_mov_b32_e32 v139, v125
	v_pk_fma_f32 v[136:137], v[138:139], v[138:139], v[136:137]
	v_mov_b32_e32 v138, v8
	v_mov_b32_e32 v139, v28
	v_pk_mul_f32 v[138:139], v[138:139], v[138:139]
	v_mov_b32_e32 v140, v9
	v_mov_b32_e32 v141, v29
	v_pk_fma_f32 v[138:139], v[140:141], v[140:141], v[138:139]
	v_mov_b32_e32 v140, v10
	v_mov_b32_e32 v141, v30
	v_pk_fma_f32 v[138:139], v[140:141], v[140:141], v[138:139]
	v_mov_b32_e32 v140, v11
	v_mov_b32_e32 v141, v31
	v_pk_fma_f32 v[138:139], v[140:141], v[140:141], v[138:139]
	v_mov_b32_e32 v140, v44
	v_mov_b32_e32 v141, v106
	v_pk_mul_f32 v[140:141], v[140:141], v[140:141]
	v_mov_b32_e32 v162, v45
	v_mov_b32_e32 v163, v107
	v_pk_fma_f32 v[140:141], v[162:163], v[162:163], v[140:141]
	v_mov_b32_e32 v162, v46
	v_mov_b32_e32 v163, v108
	v_pk_fma_f32 v[140:141], v[162:163], v[162:163], v[140:141]
	v_mov_b32_e32 v162, v47
	v_mov_b32_e32 v163, v109
	v_pk_fma_f32 v[140:141], v[162:163], v[162:163], v[140:141]
	v_mov_b32_e32 v162, v4
	v_mov_b32_e32 v163, v16
	v_pk_mul_f32 v[162:163], v[162:163], v[162:163]
	v_mov_b32_e32 v166, v5
	v_mov_b32_e32 v167, v17
	v_pk_fma_f32 v[162:163], v[166:167], v[166:167], v[162:163]
	v_mov_b32_e32 v166, v6
	v_mov_b32_e32 v167, v18
	v_pk_fma_f32 v[162:163], v[166:167], v[166:167], v[162:163]
	v_mov_b32_e32 v166, v7
	v_mov_b32_e32 v167, v19
	v_pk_fma_f32 v[162:163], v[166:167], v[166:167], v[162:163]
	v_mov_b32_e32 v166, v24
	v_mov_b32_e32 v167, v64
	v_pk_mul_f32 v[166:167], v[166:167], v[166:167]
	v_mov_b32_e32 v168, v25
	v_mov_b32_e32 v169, v65
	v_pk_fma_f32 v[166:167], v[168:169], v[168:169], v[166:167]
	v_mov_b32_e32 v168, v26
	v_mov_b32_e32 v169, v66
	v_pk_fma_f32 v[166:167], v[168:169], v[168:169], v[166:167]
	v_mov_b32_e32 v168, v27
	v_mov_b32_e32 v169, v67
	v_pk_fma_f32 v[166:167], v[168:169], v[168:169], v[166:167]
	v_mov_b32_e32 v168, v0
	v_mov_b32_e32 v169, v12
	v_pk_mul_f32 v[168:169], v[168:169], v[168:169]
	v_mov_b32_e32 v178, v1
	v_mov_b32_e32 v179, v13
	v_pk_fma_f32 v[168:169], v[178:179], v[178:179], v[168:169]
	v_mov_b32_e32 v178, v2
	v_mov_b32_e32 v179, v14
	v_pk_fma_f32 v[168:169], v[178:179], v[178:179], v[168:169]
	v_mov_b32_e32 v178, v3
	v_mov_b32_e32 v179, v15
	v_pk_fma_f32 v[168:169], v[178:179], v[178:179], v[168:169]
	v_mov_b32_e32 v178, v136
	v_mov_b32_e32 v179, v132
	v_mov_b32_e32 v132, v137
	v_pk_add_f32 v[132:133], v[178:179], v[132:133]
	v_mov_b32_e32 v136, v139
	v_mov_b32_e32 v137, v135
	v_pk_add_f32 v[132:133], v[136:137], v[132:133]
	v_mov_b32_e32 v139, v134
	v_pk_add_f32 v[132:133], v[138:139], v[132:133]
	ds_bpermute_b32 v135, v149, v133
	ds_bpermute_b32 v134, v149, v132
	v_add_u32_e32 v96, 0xffffdffd, v154
	v_lshrrev_b32_e32 v96, 11, v96
	v_add_u32_e32 v96, 1, v96
	v_cndmask_b32_e64 v96, 0, v96, s[0:1]
	s_waitcnt lgkmcnt(0)
	v_pk_add_f32 v[132:133], v[132:133], v[134:135]
	ds_bpermute_b32 v135, v151, v133
	ds_bpermute_b32 v134, v151, v132
	s_and_b64 s[0:1], exec, s[40:41]
	v_add_u32_e32 v96, s3, v96
	s_or_b64 s[30:31], s[0:1], s[30:31]
	v_mov_b64_e32 v[130:131], s[80:81]
	s_waitcnt lgkmcnt(0)
	v_pk_add_f32 v[132:133], v[132:133], v[134:135]
	ds_bpermute_b32 v135, v153, v133
	ds_bpermute_b32 v134, v153, v132
	s_mov_b32 s0, 0x9000
	v_mad_u64_u32 v[130:131], s[0:1], v96, s0, v[130:131]
	s_mov_b64 s[0:1], 0x1000
	s_waitcnt lgkmcnt(0)
	v_pk_add_f32 v[132:133], v[132:133], v[134:135]
	ds_bpermute_b32 v135, v159, v133
	ds_bpermute_b32 v134, v159, v132
	v_lshl_add_u64 v[156:157], v[130:131], 0, s[0:1]
	s_mov_b32 s0, 0x358637bd
	s_mov_b32 s36, 0x3a800000
	s_mov_b32 s24, 0x800000
	s_waitcnt lgkmcnt(0)
	v_pk_add_f32 v[132:133], v[132:133], v[134:135]
	ds_bpermute_b32 v135, v161, v133
	ds_bpermute_b32 v134, v161, v132
	v_mov_b32_e32 v136, v169
	v_mov_b32_e32 v137, v163
	v_mov_b32_e32 v169, v162
	v_add_u32_e32 v176, -3, v154
	s_waitcnt lgkmcnt(0)
	v_pk_add_f32 v[132:133], v[132:133], v[134:135]
	ds_bpermute_b32 v135, v171, v133
	ds_bpermute_b32 v134, v171, v132
	v_ashrrev_i32_e32 v177, 31, v176
	v_ashrrev_i32_e32 v155, 31, v154
	s_mov_b32 s82, 0x800000
	s_waitcnt lgkmcnt(0)
	v_pk_add_f32 v[132:133], v[132:133], v[134:135]
	v_mov_b64_e32 v[134:135], s[0:1]
	v_pk_fma_f32 v[132:133], v[132:133], s[36:37], v[134:135] op_sel_hi:[1,0,0]
	s_nop 0
	v_mul_f32_e32 v96, 0x4b800000, v133
	v_cmp_gt_f32_e64 s[0:1], s24, v133
	v_cmp_gt_f32_e32 vcc, s24, v132
	s_nop 0
	v_cndmask_b32_e64 v96, v133, v96, s[0:1]
	v_rsq_f32_e32 v96, v96
	s_nop 0
	v_mul_f32_e32 v133, 0x45800000, v96
	v_cndmask_b32_e64 v178, v96, v133, s[0:1]
	v_mul_f32_e32 v96, 0x4b800000, v132
	v_cndmask_b32_e32 v96, v132, v96, vcc
	v_rsq_f32_e32 v96, v96
	v_mov_b32_e32 v133, v140
	v_mov_b32_e32 v140, v167
	v_pk_mul_f32 v[126:127], v[126:127], v[178:179] op_sel_hi:[1,0]
	v_mul_f32_e32 v132, 0x45800000, v96
	v_cndmask_b32_e32 v174, v96, v132, vcc
	v_mov_b32_e32 v132, v166
	v_pk_add_f32 v[132:133], v[132:133], v[140:141]
	v_pk_mul_f32 v[128:129], v[128:129], v[178:179] op_sel_hi:[1,0]
	v_pk_add_f32 v[132:133], v[136:137], v[132:133]
	v_pk_mul_f32 v[122:123], v[122:123], v[174:175] op_sel_hi:[1,0]
	v_pk_add_f32 v[132:133], v[168:169], v[132:133]
	ds_bpermute_b32 v137, v149, v133
	ds_bpermute_b32 v136, v149, v132
	v_pk_mul_f32 v[124:125], v[124:125], v[174:175] op_sel_hi:[1,0]
	v_pk_mul_f32 v[72:73], v[72:73], v[174:175] op_sel_hi:[1,0]
	v_pk_mul_f32 v[74:75], v[74:75], v[174:175] op_sel_hi:[1,0]
	v_pk_mul_f32 v[28:29], v[28:29], v[174:175] op_sel_hi:[1,0]
	s_waitcnt lgkmcnt(0)
	v_pk_add_f32 v[132:133], v[132:133], v[136:137]
	ds_bpermute_b32 v137, v151, v133
	ds_bpermute_b32 v136, v151, v132
	v_pk_mul_f32 v[30:31], v[30:31], v[174:175] op_sel_hi:[1,0]
	v_pk_mul_f32 v[8:9], v[8:9], v[174:175] op_sel_hi:[1,0]
	v_pk_mul_f32 v[10:11], v[10:11], v[174:175] op_sel_hi:[1,0]
	s_waitcnt lgkmcnt(0)
	v_pk_add_f32 v[132:133], v[132:133], v[136:137]
	ds_bpermute_b32 v137, v153, v133
	ds_bpermute_b32 v136, v153, v132
	s_waitcnt lgkmcnt(0)
	v_pk_add_f32 v[132:133], v[132:133], v[136:137]
	ds_bpermute_b32 v137, v159, v133
	ds_bpermute_b32 v136, v159, v132
	s_waitcnt lgkmcnt(0)
	v_pk_add_f32 v[132:133], v[132:133], v[136:137]
	ds_bpermute_b32 v137, v161, v133
	ds_bpermute_b32 v136, v161, v132
	s_waitcnt lgkmcnt(0)
	v_pk_add_f32 v[132:133], v[132:133], v[136:137]
	ds_bpermute_b32 v137, v171, v133
	ds_bpermute_b32 v136, v171, v132
	s_waitcnt lgkmcnt(0)
	v_pk_add_f32 v[132:133], v[132:133], v[136:137]
	s_nop 0
	v_pk_fma_f32 v[132:133], v[132:133], s[36:37], v[134:135] op_sel_hi:[1,0,0]
	s_nop 0
	v_mul_f32_e32 v96, 0x4b800000, v133
	v_cmp_gt_f32_e64 s[0:1], s24, v133
	v_cmp_gt_f32_e32 vcc, s24, v132
	s_nop 0
	v_cndmask_b32_e64 v96, v133, v96, s[0:1]
	v_rsq_f32_e32 v96, v96
	s_nop 0
	v_mul_f32_e32 v133, 0x45800000, v96
	v_cndmask_b32_e64 v160, v96, v133, s[0:1]
	v_mul_f32_e32 v96, 0x4b800000, v132
	v_cndmask_b32_e32 v96, v132, v96, vcc
	v_rsq_f32_e32 v96, v96
	v_pk_mul_f32 v[106:107], v[106:107], v[160:161] op_sel_hi:[1,0]
	v_pk_mul_f32 v[108:109], v[108:109], v[160:161] op_sel_hi:[1,0]
	v_pk_mul_f32 v[44:45], v[44:45], v[160:161] op_sel_hi:[1,0]
	v_mul_f32_e32 v132, 0x45800000, v96
	v_cndmask_b32_e32 v158, v96, v132, vcc
	v_lshlrev_b32_e32 v96, 2, v142
	v_lshl_add_u64 v[132:133], v[156:157], 0, v[96:97]
	v_lshl_add_u64 v[180:181], v[130:131], 0, v[96:97]
	v_mov_b64_e32 v[232:233], v[132:133]
	global_load_dwordx4 v[134:137], v[144:145], off
	global_load_dwordx4 v[138:141], v[132:133], off
	s_nop 0
	global_load_dwordx4 v[130:133], v[180:181], off
	global_load_dwordx4 v[184:187], v[144:145], off offset:1024
	global_load_dwordx4 v[188:191], v[232:233], off offset:1024
	global_load_dwordx4 v[192:195], v[180:181], off offset:1024
	global_load_dwordx4 v[196:199], v[144:145], off offset:2048
	global_load_dwordx4 v[200:203], v[232:233], off offset:2048
	global_load_dwordx4 v[216:219], v[180:181], off offset:2048
	global_load_dwordx4 v[220:223], v[144:145], off offset:3072
	global_load_dwordx4 v[224:227], v[232:233], off offset:3072
	global_load_dwordx4 v[228:231], v[180:181], off offset:3072
	v_pk_mul_f32 v[64:65], v[64:65], v[158:159] op_sel_hi:[1,0]
	v_pk_mul_f32 v[66:67], v[66:67], v[158:159] op_sel_hi:[1,0]
	v_lshlrev_b32_e32 v96, 2, v148
	v_pk_mul_f32 v[46:47], v[46:47], v[160:161] op_sel_hi:[1,0]
	v_pk_mul_f32 v[24:25], v[24:25], v[158:159] op_sel_hi:[1,0]
	v_pk_mul_f32 v[26:27], v[26:27], v[158:159] op_sel_hi:[1,0]
	v_pk_mul_f32 v[16:17], v[16:17], v[160:161] op_sel_hi:[1,0]
	v_pk_mul_f32 v[18:19], v[18:19], v[160:161] op_sel_hi:[1,0]
	v_pk_mul_f32 v[12:13], v[12:13], v[158:159] op_sel_hi:[1,0]
	v_pk_mul_f32 v[14:15], v[14:15], v[158:159] op_sel_hi:[1,0]
	v_pk_mul_f32 v[4:5], v[4:5], v[160:161] op_sel_hi:[1,0]
	v_pk_mul_f32 v[6:7], v[6:7], v[160:161] op_sel_hi:[1,0]
	v_pk_mul_f32 v[0:1], v[0:1], v[158:159] op_sel_hi:[1,0]
	v_pk_mul_f32 v[2:3], v[2:3], v[158:159] op_sel_hi:[1,0]
	s_waitcnt vmcnt(10)
	v_pk_add_f32 v[138:139], v[138:139], 1.0 op_sel_hi:[1,0]
	s_nop 0
	v_pk_mul_f32 v[134:135], v[134:135], v[138:139]
	v_pk_add_f32 v[138:139], v[140:141], 1.0 op_sel_hi:[1,0]
	s_waitcnt vmcnt(9)
	v_pk_fma_f32 v[126:127], v[126:127], v[134:135], v[130:131]
	v_pk_mul_f32 v[136:137], v[136:137], v[138:139]
	v_pk_fma_f32 v[122:123], v[134:135], v[122:123], v[130:131]
	v_pk_fma_f32 v[128:129], v[128:129], v[136:137], v[132:133]
	v_pk_fma_f32 v[124:125], v[124:125], v[136:137], v[132:133]
	v_pk_fma_f32 v[106:107], v[134:135], v[106:107], v[130:131]
	v_pk_fma_f32 v[108:109], v[136:137], v[108:109], v[132:133]
	v_cvt_pk_bf16_f32 v126, v126, v127
	v_cvt_pk_bf16_f32 v127, v128, v129
	v_lshlrev_b64 v[128:129], 11, v[176:177]
	v_cvt_pk_bf16_f32 v122, v122, v123
	v_cvt_pk_bf16_f32 v123, v124, v125
	v_add_u32_e32 v124, -2, v154
	v_cvt_pk_bf16_f32 v106, v106, v107
	v_cvt_pk_bf16_f32 v107, v108, v109
	v_add_u32_e32 v108, -1, v154
	v_lshl_add_u64 v[138:139], v[146:147], 0, v[128:129]
	v_ashrrev_i32_e32 v125, 31, v124
	v_ashrrev_i32_e32 v109, 31, v108
	global_store_dwordx2 v[138:139], v[126:127], off
	v_lshlrev_b64 v[126:127], 11, v[124:125]
	v_lshlrev_b64 v[138:139], 11, v[108:109]
	v_pk_fma_f32 v[64:65], v[134:135], v[64:65], v[130:131]
	v_pk_fma_f32 v[66:67], v[136:137], v[66:67], v[132:133]
	v_lshlrev_b64 v[130:131], 11, v[154:155]
	v_lshl_add_u64 v[124:125], v[146:147], 0, v[126:127]
	v_lshl_add_u64 v[108:109], v[146:147], 0, v[138:139]
	v_cvt_pk_bf16_f32 v64, v64, v65
	v_cvt_pk_bf16_f32 v65, v66, v67
	v_lshl_add_u64 v[66:67], v[146:147], 0, v[130:131]
	global_store_dwordx2 v[124:125], v[122:123], off
	global_store_dwordx2 v[108:109], v[106:107], off
	global_store_dwordx2 v[66:67], v[64:65], off
	v_lshl_add_u64 v[106:107], v[156:157], 0, v[96:97]
	s_nop 0
	s_nop 0
	v_lshlrev_b32_e32 v96, 1, v148
	v_mov_b32_e32 v154, v175
	s_waitcnt vmcnt(11)
	v_pk_add_f32 v[106:107], v[188:189], 1.0 op_sel_hi:[1, 0]
	v_pk_add_f32 v[108:109], v[190:191], 1.0 op_sel_hi:[1, 0]
	v_pk_mul_f32 v[64:65], v[184:185], v[106:107]
	v_pk_mul_f32 v[106:107], v[110:111], v[178:179] op_sel_hi:[1,0]
	v_pk_mul_f32 v[66:67], v[186:187], v[108:109]
	v_pk_mul_f32 v[108:109], v[112:113], v[178:179] op_sel_hi:[1,0]
	s_waitcnt vmcnt(10)
	v_pk_fma_f32 v[106:107], v[106:107], v[64:65], v[192:193]
	v_pk_fma_f32 v[108:109], v[108:109], v[66:67], v[194:195]
	v_cvt_pk_bf16_f32 v106, v106, v107
	v_cvt_pk_bf16_f32 v107, v108, v109
	v_lshl_add_u64 v[108:109], s[22:23], 0, v[128:129]
	v_pk_fma_f32 v[72:73], v[72:73], v[64:65], v[192:193]
	v_pk_fma_f32 v[74:75], v[74:75], v[66:67], v[194:195]
	v_lshl_add_u64 v[110:111], v[108:109], 0, v[96:97]
	v_cvt_pk_bf16_f32 v72, v72, v73
	v_cvt_pk_bf16_f32 v73, v74, v75
	v_lshl_add_u64 v[74:75], s[22:23], 0, v[126:127]
	global_store_dwordx2 v[110:111], v[106:107], off
	v_lshl_add_u64 v[106:107], v[74:75], 0, v[96:97]
	global_store_dwordx2 v[106:107], v[72:73], off
	v_pk_fma_f32 v[44:45], v[44:45], v[64:65], v[192:193]
	v_pk_fma_f32 v[46:47], v[46:47], v[66:67], v[194:195]
	v_lshl_add_u64 v[72:73], s[22:23], 0, v[138:139]
	v_pk_fma_f32 v[24:25], v[24:25], v[64:65], v[192:193]
	v_pk_fma_f32 v[26:27], v[26:27], v[66:67], v[194:195]
	v_lshl_add_u64 v[106:107], s[22:23], 0, v[130:131]
	v_cvt_pk_bf16_f32 v44, v44, v45
	v_cvt_pk_bf16_f32 v45, v46, v47
	v_lshl_add_u64 v[46:47], v[72:73], 0, v[96:97]
	v_cvt_pk_bf16_f32 v24, v24, v25
	v_cvt_pk_bf16_f32 v25, v26, v27
	v_lshl_add_u64 v[26:27], v[106:107], 0, v[96:97]
	v_lshlrev_b32_e32 v96, 2, v150
	global_store_dwordx2 v[46:47], v[44:45], off
	global_store_dwordx2 v[26:27], v[24:25], off
	v_lshl_add_u64 v[44:45], v[156:157], 0, v[96:97]
	s_nop 0
	s_nop 0
	v_lshlrev_b32_e32 v96, 1, v150
	v_mov_b64_e32 v[128:129], v[34:35]
	v_mov_b64_e32 v[126:127], v[32:33]
	v_mov_b64_e32 v[124:125], v[116:117]
	v_mov_b64_e32 v[122:123], v[114:115]
	v_mov_b64_e32 v[112:113], v[38:39]
	v_mov_b64_e32 v[110:111], v[36:37]
	s_waitcnt vmcnt(12)
	v_pk_add_f32 v[44:45], v[200:201], 1.0 op_sel_hi:[1, 0]
	v_pk_add_f32 v[46:47], v[202:203], 1.0 op_sel_hi:[1, 0]
	v_pk_mul_f32 v[24:25], v[196:197], v[44:45]
	v_pk_mul_f32 v[44:45], v[52:53], v[178:179] op_sel_hi:[1,0]
	v_pk_mul_f32 v[26:27], v[198:199], v[46:47]
	v_pk_mul_f32 v[46:47], v[54:55], v[178:179] op_sel_hi:[1,0]
	s_waitcnt vmcnt(11)
	v_pk_fma_f32 v[44:45], v[44:45], v[24:25], v[216:217]
	v_pk_fma_f32 v[46:47], v[46:47], v[26:27], v[218:219]
	v_pk_fma_f32 v[28:29], v[28:29], v[24:25], v[216:217]
	v_pk_fma_f32 v[30:31], v[30:31], v[26:27], v[218:219]
	v_pk_fma_f32 v[16:17], v[16:17], v[24:25], v[216:217]
	v_pk_fma_f32 v[18:19], v[18:19], v[26:27], v[218:219]
	v_pk_fma_f32 v[12:13], v[12:13], v[24:25], v[216:217]
	v_pk_fma_f32 v[14:15], v[14:15], v[26:27], v[218:219]
	v_cvt_pk_bf16_f32 v44, v44, v45
	v_cvt_pk_bf16_f32 v45, v46, v47
	v_lshl_add_u64 v[46:47], v[108:109], 0, v[96:97]
	v_cvt_pk_bf16_f32 v28, v28, v29
	v_cvt_pk_bf16_f32 v29, v30, v31
	v_lshl_add_u64 v[30:31], v[74:75], 0, v[96:97]
	v_cvt_pk_bf16_f32 v16, v16, v17
	v_cvt_pk_bf16_f32 v17, v18, v19
	v_lshl_add_u64 v[18:19], v[72:73], 0, v[96:97]
	v_cvt_pk_bf16_f32 v12, v12, v13
	v_cvt_pk_bf16_f32 v13, v14, v15
	v_lshl_add_u64 v[14:15], v[106:107], 0, v[96:97]
	v_lshlrev_b32_e32 v96, 2, v152
	global_store_dwordx2 v[46:47], v[44:45], off
	global_store_dwordx2 v[30:31], v[28:29], off
	global_store_dwordx2 v[18:19], v[16:17], off
	global_store_dwordx2 v[14:15], v[12:13], off
	v_lshl_add_u64 v[16:17], v[156:157], 0, v[96:97]
	s_nop 0
	s_nop 0
	v_lshlrev_b32_e32 v96, 1, v152
	v_mov_b64_e32 v[66:67], v[90:91]
	v_mov_b64_e32 v[64:65], v[88:89]
	v_mov_b64_e32 v[46:47], v[78:79]
	v_mov_b64_e32 v[44:45], v[76:77]
	v_mov_b64_e32 v[54:55], v[42:43]
	v_mov_b64_e32 v[52:53], v[40:41]
	v_mov_b64_e32 v[30:31], v[62:63]
	v_mov_b64_e32 v[28:29], v[60:61]
	s_waitcnt vmcnt(13)
	v_pk_add_f32 v[16:17], v[224:225], 1.0 op_sel_hi:[1, 0]
	v_pk_add_f32 v[18:19], v[226:227], 1.0 op_sel_hi:[1, 0]
	v_pk_mul_f32 v[12:13], v[220:221], v[16:17]
	v_pk_mul_f32 v[16:17], v[20:21], v[178:179] op_sel_hi:[1,0]
	v_pk_mul_f32 v[14:15], v[222:223], v[18:19]
	v_pk_mul_f32 v[18:19], v[22:23], v[178:179] op_sel_hi:[1,0]
	s_waitcnt vmcnt(12)
	v_pk_fma_f32 v[16:17], v[16:17], v[12:13], v[228:229]
	v_pk_fma_f32 v[18:19], v[18:19], v[14:15], v[230:231]
	v_pk_fma_f32 v[8:9], v[8:9], v[12:13], v[228:229]
	v_pk_fma_f32 v[10:11], v[10:11], v[14:15], v[230:231]
	v_pk_fma_f32 v[4:5], v[4:5], v[12:13], v[228:229]
	v_pk_fma_f32 v[6:7], v[6:7], v[14:15], v[230:231]
	v_pk_fma_f32 v[0:1], v[0:1], v[12:13], v[228:229]
	v_pk_fma_f32 v[2:3], v[2:3], v[14:15], v[230:231]
	v_cvt_pk_bf16_f32 v16, v16, v17
	v_cvt_pk_bf16_f32 v17, v18, v19
	v_lshl_add_u64 v[18:19], v[108:109], 0, v[96:97]
	v_cvt_pk_bf16_f32 v8, v8, v9
	v_cvt_pk_bf16_f32 v9, v10, v11
	v_lshl_add_u64 v[10:11], v[74:75], 0, v[96:97]
	v_cvt_pk_bf16_f32 v4, v4, v5
	v_cvt_pk_bf16_f32 v5, v6, v7
	v_lshl_add_u64 v[6:7], v[72:73], 0, v[96:97]
	v_cvt_pk_bf16_f32 v0, v0, v1
	v_cvt_pk_bf16_f32 v1, v2, v3
	v_lshl_add_u64 v[2:3], v[106:107], 0, v[96:97]
	global_store_dwordx2 v[18:19], v[16:17], off
	global_store_dwordx2 v[10:11], v[8:9], off
	global_store_dwordx2 v[6:7], v[4:5], off
	global_store_dwordx2 v[2:3], v[0:1], off
	v_mov_b64_e32 v[108:109], v[70:71]
	v_mov_b64_e32 v[106:107], v[68:69]
	v_mov_b64_e32 v[74:75], v[58:59]
	v_mov_b64_e32 v[72:73], v[56:57]
	v_mov_b64_e32 v[26:27], v[94:95]
	v_mov_b64_e32 v[24:25], v[92:93]
	v_mov_b64_e32 v[18:19], v[82:83]
	v_mov_b64_e32 v[16:17], v[80:81]
	v_mov_b64_e32 v[14:15], v[104:105]
	v_mov_b64_e32 v[12:13], v[102:103]
	v_mov_b64_e32 v[22:23], v[50:51]
	v_mov_b64_e32 v[20:21], v[48:49]
	v_mov_b64_e32 v[10:11], v[100:101]
	v_mov_b64_e32 v[8:9], v[98:99]
	v_mov_b64_e32 v[6:7], v[86:87]
	v_mov_b64_e32 v[4:5], v[84:85]
	v_mov_b64_e32 v[2:3], v[120:121]
	v_mov_b64_e32 v[0:1], v[118:119]
	s_andn2_b64 exec, exec, s[30:31]
	s_cbranch_execz .LBB0_554
